# version 97 plus one static s_setprio 1 for the trailing half (waves 4-7) in each GEMM phase, reset at the phase loop head
# baseline (speedup 1.0000x reference)
; __device__ __forceinline__ int sub_of(int ph) { const int j = (ph - 1) & 7; return (j < 3) ? j : (j == 3 ? 7 : j - 1); }
; __device__ __forceinline__ void xcd_barrier(const XcdBarrier& b) {
;     asm volatile("s_waitcnt vmcnt(0)" ::: "memory");
;     __syncthreads();
;     if (threadIdx.x == 0) {
;         unsigned* bar = b.bar;
;         __builtin_amdgcn_s_waitcnt(0);
;         unsigned nloc = b.st[0], nx = b.st[1];
;         if (nloc == 0u) { xcd_barrier_complete(bar, b.x, nloc, nx); b.st[0] = nloc; b.st[1] = nx; }
; __global__ void __launch_bounds__(NTHREADS, 2) mk_fwd(Args args) {
;     ...
;     for (int si = 2 * lo; si < 2 * hi; ++si) {
;         const int ph = si >> 1;
;         if (si & 1) {
;             bool dup = false;
;     ...
;             dup = dup || (ph == 0);
;     ...
;             dup = dup || (ph >= 1 && ph < N_PHASES - 1 && sub_of(ph) == 3);
;     ...
;             dup = dup || (ph >= 1 && ph < N_PHASES - 1 && (sub_of(ph) == 0 || sub_of(ph) == 5));
;     ...
;             dup = dup || (ph >= 1 && ph < N_PHASES - 1 && (sub_of(ph) == 1 || sub_of(ph) == 4 || sub_of(ph) == 6));
;     ...
;             dup = dup || (ph >= 1 && ph < N_PHASES - 1 && sub_of(ph) == 2);
;     ...
;             if (!dup) continue;
;         }
;         if (!first) xcd_barrier(bar);
.LBB0_17:
	s_setprio 0
	s_bitcmp1_b32 s90, 0
	s_cselect_b64 s[0:1], -1, 0
	s_and_b64 vcc, exec, s[0:1]
	s_cbranch_vccnz .LBB0_16
	s_xor_b64 s[0:1], s[4:5], -1
	s_andn2_b64 vcc, exec, s[0:1]
	s_cbranch_vccnz .LBB0_68
	s_waitcnt vmcnt(0)
	s_barrier
	s_mov_b64 s[0:1], exec
	v_readlane_b32 s4, v253, 17
	v_readlane_b32 s5, v253, 18
	s_and_b64 s[4:5], s[0:1], s[4:5]
	s_mov_b64 exec, s[4:5]
	s_cbranch_execz .LBB0_67
	v_mov_b32_e32 v2, s59
	s_waitcnt vmcnt(0) expcnt(0) lgkmcnt(0)
	ds_read_b32 v5, v2
	ds_read_b32 v2, v2 offset:4
	s_waitcnt lgkmcnt(1)
	v_cmp_ne_u32_e32 vcc, 0, v5
	s_cbranch_vccnz .LBB0_35
	s_load_dwordx2 s[4:5], s[56:57], 0x4
	s_mov_b32 s10, 1
	s_waitcnt lgkmcnt(0)
	s_mul_i32 s3, s4, s58
	s_mul_i32 s3, s3, s5
	s_branch .LBB0_23

; #define PG8_STAGE(bufoff, gbase, voff) do { _Pragma("unroll") for (int _i = 0; _i < 2; ++_i) \
;         __builtin_amdgcn_global_load_lds((const unsigned*)((const char*)(gbase) + (voff)[_i]), (PG8_LAS unsigned*)(lds + (bufoff) + ldsw + _i * 8192), 16, 0, 0); } while (0)
; #define PG8_BAR __builtin_amdgcn_s_barrier()
; template <class Epi, class Sched, bool ALIGN_EPI = false, bool SP2 = false>
; __device__ __forceinline__ void gemm_phase(PG8_LAS unsigned char* lds, const Gemm g, const Sched& S, const Epi& E, const int tid_in) {
;     ...
;     for (int i = 0; i < 2; ++i) { int R, C; stage_rc(tid * 16 + i * 8192, R, C); const int Rb = Epi::PERM ? ((R & ~31) + perm32(R & 31)) : R;
;         voffA[i] = (unsigned)(R * K + C) * 2u; voffB[i] = (unsigned)(Rb * K + C) * 2u; }
;     const size_t kstep = (size_t)(BK * 2);
;     const size_t hstep = (size_t)HALF * K * 2;
;     const size_t tstep = 2 * hstep;
;     const unsigned ldsw = (unsigned)wid * 1024u;
;     const int aoff = lds_byte(wr * 64 + fr, fq * 8), boff = lds_byte(wc * 32 + fr, fq * 8);
;     ...
;     Unit cur, nxt; int ui = 0;
;     if (!S.next(0, cur)) return;
;     f32x4 acc[2][2][4][2];
; #pragma unroll
;     for (int a = 0; a < 2; ++a)
; #pragma unroll
;         for (int b = 0; b < 2; ++b)
; #pragma unroll
;             for (int m = 0; m < 4; ++m)
; #pragma unroll
;                 for (int n = 0; n < 2; ++n) acc[a][b][m][n] = (f32x4){0.f, 0.f, 0.f, 0.f};
;     bf16x8 At[4][2], B0[2][2], B1[2][2];
;     const char* cA = (const char*)g.A + (size_t)cur.pm * tstep; const char* cB = (const char*)g.Bt + (size_t)cur.pn * tstep;
;     S.a_ready(cur);
;     if constexpr (SP2) {
;         PG8_STAGE(PG8_SB(0, 0), cB, voffB); PG8_STAGE(PG8_SB(0, 1), cB + hstep, voffB); PG8_STAGE(PG8_SA(0, 0), cA, voffA); PG8_STAGE(PG8_SA(0, 1), cA + hstep, voffA);
;         if (wr == 1) PG8_BAR;
.LBB0_80:
	s_and_b64 vcc, exec, s[0:1]
	s_cbranch_vccnz .LBB0_564
	v_ashrrev_i32_e32 v2, 31, v244
	v_lshrrev_b32_e32 v2, 26, v2
	v_add_u32_e32 v2, v244, v2
	s_waitcnt vmcnt(5)
	v_ashrrev_i32_e32 v14, 6, v2
	v_bfe_i32 v2, v244, 27, 1
	v_lshlrev_b32_e32 v3, 4, v244
	v_lshrrev_b32_e32 v2, 22, v2
	v_add_u32_e32 v2, v3, v2
	v_and_b32_e32 v2, 0xfffffc00, v2
	v_sub_u32_e32 v2, v3, v2
	v_lshrrev_b32_e32 v5, 4, v2
	v_bitop3_b32 v2, v5, v2, 32 bitop3:0x6c
	s_waitcnt vmcnt(0)
	v_ashrrev_i32_e32 v6, 31, v2
	v_lshrrev_b32_e32 v6, 26, v6
	v_add_u32_e32 v6, v2, v6
	v_lshlrev_b32_e32 v5, 3, v14
	s_waitcnt lgkmcnt(6)
	v_ashrrev_i32_e32 v15, 6, v6
	v_and_b32_e32 v6, 0xc0, v6
	v_and_b32_e32 v5, -16, v5
	v_sub_u32_e32 v2, v2, v6
	s_add_u32 s3, s19, 0x1080000
	v_readlane_b32 s0, v254, 54
	v_add_u32_e32 v5, v15, v5
	s_waitcnt lgkmcnt(0)
	v_lshlrev_b32_e32 v7, 5, v14
	v_ashrrev_i16_sdwa v2, v230, sext(v2) dst_sel:DWORD dst_unused:UNUSED_PAD src0_sel:DWORD src1_sel:BYTE_0
	s_addc_u32 s18, s0, 0
	v_and_b32_e32 v7, 32, v7
	v_bfe_i32 v16, v2, 0, 16
	v_lshlrev_b32_e32 v2, 1, v5
	v_lshrrev_b32_e32 v6, 2, v5
	v_and_b32_e32 v8, 3, v15
	s_mov_b32 s0, 0x1fffe0
	v_and_b32_e32 v2, 24, v2
	v_and_b32_e32 v6, 4, v6
	v_and_or_b32 v8, v5, s0, v8
	v_add_lshl_u32 v7, v7, v16, 1
	v_add_u32_e32 v3, 0x2000, v3
	v_or3_b32 v6, v8, v6, v2
	v_lshl_add_u32 v2, v5, 11, v7
	v_ashrrev_i32_e32 v5, 31, v3
	v_lshrrev_b32_e32 v5, 22, v5
	v_add_u32_e32 v5, v3, v5
	v_ashrrev_i32_e32 v17, 10, v5
	v_mul_i32_i24_e32 v5, 0x400, v17
	v_sub_u32_e32 v3, v3, v5
	v_lshrrev_b32_e32 v5, 4, v3
	v_bitop3_b32 v3, v5, v3, 32 bitop3:0x6c
	v_lshl_add_u32 v134, v6, 11, v7
	v_ashrrev_i32_e32 v6, 31, v3
	v_lshrrev_b32_e32 v6, 26, v6
	v_lshlrev_b32_e32 v5, 3, v17
	v_add_u32_e32 v6, v3, v6
	v_and_b32_e32 v5, -16, v5
	v_ashrrev_i32_e32 v18, 6, v6
	v_add_u32_e32 v5, v18, v5
	v_and_b32_e32 v6, 0xc0, v6
	v_and_b32_e32 v8, 3, v18
	s_ashr_i32 s16, s8, 6
	s_ashr_i32 s39, s38, 31
	s_ashr_i32 s11, s10, 31
	s_mov_b32 s49, s19
	s_ashr_i32 s9, s8, 8
	v_sub_u32_e32 v3, v3, v6
	v_and_or_b32 v8, v5, s0, v8
	s_lshl_b32 s19, s16, 10
	s_lshl_b64 s[0:1], s[38:39], 19
	s_lshl_b64 s[6:7], s[10:11], 19
	v_ashrrev_i16_sdwa v3, v230, sext(v3) dst_sel:DWORD dst_unused:UNUSED_PAD src0_sel:DWORD src1_sel:BYTE_0
	s_add_u32 s12, s3, s6
	v_lshlrev_b32_e32 v7, 5, v17
	v_bfe_i32 v19, v3, 0, 16
	v_lshlrev_b32_e32 v3, 1, v5
	v_lshrrev_b32_e32 v6, 2, v5
	s_addc_u32 s13, s18, s7
	s_add_i32 s22, s19, 0
	v_and_b32_e32 v7, 32, v7
	v_and_b32_e32 v3, 24, v3
	v_and_b32_e32 v6, 4, v6
	s_add_i32 m0, s22, 0x10000
	v_or3_b32 v3, v8, v6, v3
	v_add_lshl_u32 v6, v7, v19, 1
	global_load_lds_dwordx4 v134, s[12:13]
	s_add_i32 m0, s22, 0x12000
	v_lshl_add_u32 v138, v3, 11, v6
	s_add_u32 s6, s12, 0x40000
	global_load_lds_dwordx4 v138, s[12:13]
	s_addc_u32 s7, s13, 0
	s_add_i32 m0, s22, 0x14000
	v_lshl_add_u32 v136, v5, 11, v6
	global_load_lds_dwordx4 v134, s[6:7]
	s_add_i32 m0, s22, 0x16000
	s_add_u32 s14, s84, s0
	s_addc_u32 s15, s85, s1
	s_add_i32 s23, s22, 0x2000
	global_load_lds_dwordx4 v138, s[6:7]
	s_mov_b32 m0, s22
	s_add_u32 s0, s14, 0x40000
	global_load_lds_dwordx4 v2, s[14:15]
	s_mov_b32 m0, s23
	s_addc_u32 s1, s15, 0
	s_add_i32 s26, s22, 0x4000
	global_load_lds_dwordx4 v136, s[14:15]
	s_mov_b32 m0, s26
	s_add_i32 s27, s22, 0x6000
	global_load_lds_dwordx4 v2, s[0:1]
	s_mov_b32 m0, s27
	v_mov_b32_e32 v135, v4
	global_load_lds_dwordx4 v136, s[0:1]
	v_mov_b32_e32 v139, v4
	v_mov_b32_e32 v3, v4
	v_mov_b32_e32 v137, v4
	s_cmp_eq_u32 s9, 1
	v_lshl_add_u64 v[12:13], s[12:13], 0, v[134:135]
	v_lshl_add_u64 v[10:11], s[12:13], 0, v[138:139]
	v_lshl_add_u64 v[6:7], s[14:15], 0, v[2:3]
	s_cselect_b64 s[0:1], -1, 0
	s_cmp_lg_u32 s9, 1
	v_lshl_add_u64 v[8:9], s[14:15], 0, v[136:137]
	s_cbranch_scc1 .LBB0_83
	s_barrier
	s_setprio 1

; #define PG8_STAGE(bufoff, gbase, voff) do { _Pragma("unroll") for (int _i = 0; _i < 2; ++_i) \
;         __builtin_amdgcn_global_load_lds((const unsigned*)((const char*)(gbase) + (voff)[_i]), (PG8_LAS unsigned*)(lds + (bufoff) + ldsw + _i * 8192), 16, 0, 0); } while (0)
; #define PG8_BAR __builtin_amdgcn_s_barrier()
; template <class Epi, class Sched, bool ALIGN_EPI = false, bool SP2 = false>
; __device__ __forceinline__ void gemm_phase(PG8_LAS unsigned char* lds, const Gemm g, const Sched& S, const Epi& E, const int tid_in) {
;     ...
;     for (int i = 0; i < 2; ++i) { int R, C; stage_rc(tid * 16 + i * 8192, R, C); const int Rb = Epi::PERM ? ((R & ~31) + perm32(R & 31)) : R;
;         voffA[i] = (unsigned)(R * K + C) * 2u; voffB[i] = (unsigned)(Rb * K + C) * 2u; }
;     const size_t kstep = (size_t)(BK * 2);
;     const size_t hstep = (size_t)HALF * K * 2;
;     const size_t tstep = 2 * hstep;
;     const unsigned ldsw = (unsigned)wid * 1024u;
;     const int aoff = lds_byte(wr * 64 + fr, fq * 8), boff = lds_byte(wc * 32 + fr, fq * 8);
;     ...
;     Unit cur, nxt; int ui = 0;
;     if (!S.next(0, cur)) return;
;     f32x4 acc[2][2][4][2];
; #pragma unroll
;     for (int a = 0; a < 2; ++a)
; #pragma unroll
;         for (int b = 0; b < 2; ++b)
; #pragma unroll
;             for (int m = 0; m < 4; ++m)
; #pragma unroll
;                 for (int n = 0; n < 2; ++n) acc[a][b][m][n] = (f32x4){0.f, 0.f, 0.f, 0.f};
;     bf16x8 At[4][2], B0[2][2], B1[2][2];
;     const char* cA = (const char*)g.A + (size_t)cur.pm * tstep; const char* cB = (const char*)g.Bt + (size_t)cur.pn * tstep;
;     S.a_ready(cur);
;     if constexpr (SP2) {
;         PG8_STAGE(PG8_SB(0, 0), cB, voffB); PG8_STAGE(PG8_SB(0, 1), cB + hstep, voffB); PG8_STAGE(PG8_SA(0, 0), cA, voffA); PG8_STAGE(PG8_SA(0, 1), cA + hstep, voffA);
;         if (wr == 1) PG8_BAR;
.LBB0_145:
	v_readlane_b32 s4, v252, 0
	s_cmp_eq_u32 s74, 0
	v_readlane_b32 s5, v252, 1
	s_cselect_b64 s[0:1], -1, 0
	s_andn2_b64 vcc, exec, s[4:5]
	v_readfirstlane_b32 s8, v244
	s_cbranch_vccnz .LBB0_186
	v_lshlrev_b32_e32 v3, 4, v244
	v_add_u32_e32 v2, 0x2000, v3
	s_waitcnt vmcnt(6)
	v_ashrrev_i32_e32 v5, 31, v2
	v_lshrrev_b32_e32 v5, 22, v5
	v_add_u32_e32 v5, v2, v5
	s_waitcnt vmcnt(1)
	v_ashrrev_i32_e32 v10, 10, v5
	v_mul_i32_i24_e32 v5, 0x400, v10
	v_sub_u32_e32 v2, v2, v5
	v_lshrrev_b32_e32 v5, 4, v2
	v_bitop3_b32 v2, v5, v2, 32 bitop3:0x6c
	v_ashrrev_i32_e32 v5, 31, v2
	v_lshrrev_b32_e32 v5, 26, v5
	s_and_b64 s[4:5], s[0:1], exec
	v_add_u32_e32 v5, v2, v5
	s_waitcnt vmcnt(0)
	v_lshlrev_b32_e32 v6, 3, v10
	s_cselect_b32 s3, 0, 0x1900000
	v_ashrrev_i32_e32 v11, 6, v5
	v_and_b32_e32 v6, -16, v6
	s_add_u32 s3, s19, s3
	v_readlane_b32 s4, v254, 54
	v_add_u32_e32 v6, v11, v6
	s_addc_u32 s16, s4, 0
	s_waitcnt lgkmcnt(0)
	v_and_b32_e32 v7, 3, v11
	s_mov_b32 s4, 0x1fffe0
	v_lshrrev_b32_e32 v8, 2, v6
	s_waitcnt lgkmcnt(0)
	v_lshlrev_b32_e32 v9, 1, v6
	v_and_b32_e32 v5, 0xc0, v5
	v_and_or_b32 v7, v6, s4, v7
	v_and_b32_e32 v8, 4, v8
	v_and_b32_e32 v9, 24, v9
	v_sub_u32_e32 v2, v2, v5
	v_or3_b32 v7, v7, v8, v9
	v_lshlrev_b32_e32 v8, 5, v10
	v_ashrrev_i16_sdwa v2, v230, sext(v2) dst_sel:DWORD dst_unused:UNUSED_PAD src0_sel:DWORD src1_sel:BYTE_0
	v_and_b32_e32 v8, 32, v8
	v_bfe_i32 v12, v2, 0, 16
	v_add_lshl_u32 v5, v8, v12, 1
	v_lshl_add_u32 v2, v7, 11, v5
	v_lshl_add_u32 v134, v6, 11, v5
	v_bfe_i32 v5, v244, 27, 1
	v_lshrrev_b32_e32 v5, 22, v5
	v_add_u32_e32 v5, v3, v5
	v_and_b32_e32 v5, 0xfffffc00, v5
	v_sub_u32_e32 v3, v3, v5
	v_lshrrev_b32_e32 v5, 4, v3
	v_ashrrev_i32_e32 v6, 31, v244
	v_bitop3_b32 v3, v5, v3, 32 bitop3:0x6c
	v_lshrrev_b32_e32 v6, 26, v6
	v_ashrrev_i32_e32 v5, 31, v3
	v_add_u32_e32 v6, v244, v6
	v_lshrrev_b32_e32 v5, 26, v5
	v_ashrrev_i32_e32 v14, 6, v6
	v_add_u32_e32 v5, v3, v5
	v_lshlrev_b32_e32 v6, 3, v14
	v_ashrrev_i32_e32 v13, 6, v5
	v_and_b32_e32 v6, -16, v6
	v_add_u32_e32 v6, v13, v6
	v_and_b32_e32 v7, 3, v13
	v_lshrrev_b32_e32 v8, 2, v6
	v_lshlrev_b32_e32 v9, 1, v6
	v_and_b32_e32 v5, 0xc0, v5
	s_ashr_i32 s10, s8, 6
	v_and_or_b32 v7, v6, s4, v7
	v_and_b32_e32 v8, 4, v8
	v_and_b32_e32 v9, 24, v9
	v_sub_u32_e32 v3, v3, v5
	s_ashr_i32 s9, s8, 8
	s_lshl_b32 s17, s10, 10
	v_or3_b32 v7, v7, v8, v9
	v_lshlrev_b32_e32 v8, 5, v14
	v_ashrrev_i16_sdwa v3, v230, sext(v3) dst_sel:DWORD dst_unused:UNUSED_PAD src0_sel:DWORD src1_sel:BYTE_0
	v_readlane_b32 s4, v252, 55
	v_and_b32_e32 v8, 32, v8
	v_bfe_i32 v15, v3, 0, 16
	v_readlane_b32 s5, v252, 56
	s_add_u32 s12, s3, s4
	v_add_lshl_u32 v3, v8, v15, 1
	s_addc_u32 s13, s16, s5
	s_add_i32 s18, s17, 0
	v_lshl_add_u32 v136, v7, 11, v3
	s_add_i32 m0, s18, 0x10000
	v_lshl_add_u32 v138, v6, 11, v3
	global_load_lds_dwordx4 v136, s[12:13]
	s_add_i32 m0, s18, 0x12000
	s_add_u32 s4, s12, 0x40000
	global_load_lds_dwordx4 v2, s[12:13]
	s_addc_u32 s5, s13, 0
	s_add_i32 m0, s18, 0x14000
	s_add_i32 s19, s18, 0x2000
	global_load_lds_dwordx4 v136, s[4:5]
	s_add_i32 m0, s18, 0x16000
	s_add_i32 s22, s18, 0x4000
	global_load_lds_dwordx4 v2, s[4:5]
	v_readlane_b32 s4, v252, 59
	s_mov_b32 m0, s18
	v_readlane_b32 s5, v252, 60
	s_add_i32 s23, s18, 0x6000
	v_mov_b32_e32 v137, v4
	v_mov_b32_e32 v3, v4
	s_cmp_eq_u32 s9, 1
	v_lshl_add_u64 v[6:7], s[12:13], 0, v[136:137]
	global_load_lds_dwordx4 v138, s[4:5]
	s_mov_b32 m0, s19
	v_lshl_add_u64 v[8:9], s[12:13], 0, v[2:3]
	global_load_lds_dwordx4 v134, s[4:5]
	v_readlane_b32 s4, v252, 61
	s_mov_b32 m0, s22
	v_readlane_b32 s5, v252, 62
	s_nop 4
	global_load_lds_dwordx4 v138, s[4:5]
	s_mov_b32 m0, s23
	s_nop 0
	global_load_lds_dwordx4 v134, s[4:5]
	s_cselect_b64 s[4:5], -1, 0
	s_cmp_lg_u32 s9, 1
	s_cbranch_scc1 .LBB0_148
	s_barrier
	s_setprio 1

; #define PG8_STAGE(bufoff, gbase, voff) do { _Pragma("unroll") for (int _i = 0; _i < 2; ++_i) \
;         __builtin_amdgcn_global_load_lds((const unsigned*)((const char*)(gbase) + (voff)[_i]), (PG8_LAS unsigned*)(lds + (bufoff) + ldsw + _i * 8192), 16, 0, 0); } while (0)
; #define PG8_LDA(dst, b, h) do { _Pragma("unroll") for (int m = 0; m < 4; ++m) _Pragma("unroll") for (int k = 0; k < 2; ++k) dst[m][k] = *(const PG8_LAS bf16x8*)(lds + PG8_SA(b, h) + aoff + m * 2048 + k * 1024); } while (0)
; #define PG8_LDB(dst, b, h) do { _Pragma("unroll") for (int n = 0; n < 2; ++n) _Pragma("unroll") for (int k = 0; k < 2; ++k) dst[n][k] = *(const PG8_LAS bf16x8*)(lds + PG8_SB(b, h) + boff + n * 2048 + k * 1024); } while (0)
; #define PG8_WAIT_V(n) asm volatile("s_waitcnt vmcnt(" #n ")" ::: "memory")
; #define PG8_WAIT_L(n) asm volatile("s_waitcnt lgkmcnt(" #n ")" ::: "memory")
; #define PG8_BAR __builtin_amdgcn_s_barrier()
; #define PG8_SCHED __builtin_amdgcn_sched_barrier(0)
; template <class Epi, class Sched, bool ALIGN_EPI = false, bool SP2 = false>
; __device__ __forceinline__ void gemm_phase(PG8_LAS unsigned char* lds, const Gemm g, const Sched& S, const Epi& E, const int tid_in) {
;     ...
;         const char* nA = has_next ? (const char*)g.A + (size_t)nxt.pm * tstep : cA; const char* nB = has_next ? (const char*)g.Bt + (size_t)nxt.pn * tstep : cB;
;         for (int t = 0; t < nt; t += 2) {
;             const bool last = (t == nt - 2);
;             const char* a1 = cA + (size_t)(t + 1) * kstep;
;             const char* a2 = last ? nA : cA + (size_t)(t + 2) * kstep; const char* b2 = last ? nB : cB + (size_t)(t + 2) * kstep;
;             const char* a3 = a2 + kstep; const char* b3 = b2 + kstep;
;             if (last && has_next) S.a_ready(nxt);
;             if constexpr (SP2) {
;             PG8_LDB(B0, 0, 0); PG8_LDB(B1, 0, 1); PG8_SCHED; PG8_LDA(At, 0, 0); PG8_STAGE(PG8_SA(1, 1), a1 + hstep, voffA);
;             PG8_WAIT_V(8); PG8_WAIT_L(0); PG8_BAR; PG8_MMA(0, 0, At, B0); PG8_MMA(0, 1, At, B1); PG8_BAR; PG8_SCHED;
;             PG8_LDA(At, 0, 1); PG8_STAGE(PG8_SB(0, 0), b2, voffB); PG8_STAGE(PG8_SB(0, 1), b2 + hstep, voffB); PG8_STAGE(PG8_SA(0, 0), a2, voffA);
;             PG8_WAIT_V(8); PG8_WAIT_L(0); PG8_BAR; PG8_MMA(1, 0, At, B0); PG8_MMA(1, 1, At, B1); PG8_BAR; PG8_SCHED;
.LBB0_153:
	s_ashr_i32 s25, s24, 31
	s_lshl_b64 s[14:15], s[24:25], 19
	s_add_u32 s34, s84, s14
	s_addc_u32 s35, s85, s15
	s_and_b64 s[14:15], s[36:37], exec
	s_cselect_b32 s25, s35, s11
	s_cselect_b32 s41, s34, s10
	s_ashr_i32 s21, s20, 31
	s_lshl_b64 s[14:15], s[20:21], 19
	s_add_u32 s38, s3, s14
	s_addc_u32 s39, s16, s15
	s_and_b64 s[14:15], s[36:37], exec
	s_cselect_b32 s21, s39, s13
	s_cselect_b32 s42, s38, s12
	s_add_u32 s10, s10, 0x40080
	s_addc_u32 s11, s11, 0
	s_add_u32 s43, s12, 0x100
	s_addc_u32 s44, s13, 0
	s_mov_b32 s45, -2
	s_add_u32 s12, s10, 0xfffc0080
	s_addc_u32 s13, s11, -1
	s_add_i32 s46, 0, 0x10000
	s_cmp_eq_u32 s45, 12
	s_cselect_b32 s15, s25, s13
	s_cselect_b32 s14, s41, s12
	v_add_u32_e32 v144, s46, v146
	s_cselect_b32 s13, s21, s44
	s_cselect_b32 s12, s42, s43
	s_add_i32 s48, 0, 0x14000
	ds_read_b128 v[150:153], v144
	ds_read_b128 v[154:157], v144 offset:1024
	ds_read_b128 v[158:161], v144 offset:2048
	ds_read_b128 v[162:165], v144 offset:3072
	v_add_u32_e32 v144, s48, v146
	ds_read_b128 v[166:169], v144
	ds_read_b128 v[170:173], v144 offset:1024
	ds_read_b128 v[174:177], v144 offset:2048
	ds_read_b128 v[178:181], v144 offset:3072
	v_lshl_add_u64 v[144:145], s[10:11], 0, v[140:141]
	s_add_i32 m0, s18, 0xc000
	ds_read_b128 v[182:185], v148
	ds_read_b128 v[186:189], v148 offset:1024
	ds_read_b128 v[190:193], v148 offset:2048
	ds_read_b128 v[198:201], v148 offset:3072
	ds_read_b128 v[202:205], v148 offset:4096
	ds_read_b128 v[206:209], v148 offset:5120
	ds_read_b128 v[210:213], v148 offset:6144
	ds_read_b128 v[214:217], v148 offset:7168
	global_load_lds_dwordx4 v[144:145], off
	v_lshl_add_u64 v[144:145], s[10:11], 0, v[142:143]
	s_add_i32 m0, s18, 0xe000
	s_nop 0
	global_load_lds_dwordx4 v[144:145], off
	s_nop 0
	s_nop 0
	s_waitcnt vmcnt(8)
	s_waitcnt lgkmcnt(0)
	s_barrier
	v_mfma_f32_16x16x32_bf16 v[130:133], v[150:153], v[182:185], 0
	v_mfma_f32_16x16x32_bf16 v[130:133], v[154:157], v[186:189], v[130:133]
	v_mfma_f32_16x16x32_bf16 v[114:117], v[150:153], v[190:193], 0
	v_mfma_f32_16x16x32_bf16 v[114:117], v[154:157], v[198:201], v[114:117]
	v_mfma_f32_16x16x32_bf16 v[98:101], v[150:153], v[202:205], 0
	v_mfma_f32_16x16x32_bf16 v[98:101], v[154:157], v[206:209], v[98:101]
	v_mfma_f32_16x16x32_bf16 v[82:85], v[150:153], v[210:213], 0
	v_mfma_f32_16x16x32_bf16 v[82:85], v[154:157], v[214:217], v[82:85]
	v_mfma_f32_16x16x32_bf16 v[126:129], v[158:161], v[182:185], 0
	v_mfma_f32_16x16x32_bf16 v[126:129], v[162:165], v[186:189], v[126:129]
	v_mfma_f32_16x16x32_bf16 v[106:109], v[158:161], v[190:193], 0
	v_mfma_f32_16x16x32_bf16 v[106:109], v[162:165], v[198:201], v[106:109]
	v_mfma_f32_16x16x32_bf16 v[94:97], v[158:161], v[202:205], 0
	v_mfma_f32_16x16x32_bf16 v[94:97], v[162:165], v[206:209], v[94:97]
	v_mfma_f32_16x16x32_bf16 v[78:81], v[158:161], v[210:213], 0
	v_mfma_f32_16x16x32_bf16 v[78:81], v[162:165], v[214:217], v[78:81]
	v_mfma_f32_16x16x32_bf16 v[122:125], v[166:169], v[182:185], 0
	v_mfma_f32_16x16x32_bf16 v[122:125], v[170:173], v[186:189], v[122:125]
	v_mfma_f32_16x16x32_bf16 v[110:113], v[166:169], v[190:193], 0
	v_mfma_f32_16x16x32_bf16 v[110:113], v[170:173], v[198:201], v[110:113]
	v_mfma_f32_16x16x32_bf16 v[90:93], v[166:169], v[202:205], 0
	v_mfma_f32_16x16x32_bf16 v[90:93], v[170:173], v[206:209], v[90:93]
	v_mfma_f32_16x16x32_bf16 v[74:77], v[166:169], v[210:213], 0
	v_mfma_f32_16x16x32_bf16 v[74:77], v[170:173], v[214:217], v[74:77]
	v_mfma_f32_16x16x32_bf16 v[118:121], v[174:177], v[182:185], 0
	v_mfma_f32_16x16x32_bf16 v[118:121], v[178:181], v[186:189], v[118:121]
	v_mfma_f32_16x16x32_bf16 v[102:105], v[174:177], v[190:193], 0
	v_mfma_f32_16x16x32_bf16 v[102:105], v[178:181], v[198:201], v[102:105]
	v_mfma_f32_16x16x32_bf16 v[86:89], v[174:177], v[202:205], 0
	v_mfma_f32_16x16x32_bf16 v[86:89], v[178:181], v[206:209], v[86:89]
	v_mfma_f32_16x16x32_bf16 v[70:73], v[174:177], v[210:213], 0
	v_mfma_f32_16x16x32_bf16 v[70:73], v[178:181], v[214:217], v[70:73]
	s_barrier
	s_add_i32 s46, s46, s17
	v_lshl_add_u64 v[144:145], s[12:13], 0, v[136:137]
	s_mov_b32 m0, s46
	ds_read_b128 v[182:185], v148 offset:16384
	ds_read_b128 v[186:189], v148 offset:17408
	ds_read_b128 v[190:193], v148 offset:18432
	ds_read_b128 v[198:201], v148 offset:19456
	ds_read_b128 v[202:205], v148 offset:20480
	ds_read_b128 v[206:209], v148 offset:21504
	ds_read_b128 v[210:213], v148 offset:22528
	ds_read_b128 v[214:217], v148 offset:23552
	global_load_lds_dwordx4 v[144:145], off
	s_add_i32 m0, s46, 0x2000
	s_add_u32 s46, s12, 0x40000
	v_lshl_add_u64 v[218:219], s[12:13], 0, v[2:3]
	s_addc_u32 s47, s13, 0
	s_add_i32 s48, s48, s17
	global_load_lds_dwordx4 v[218:219], off
	v_lshl_add_u64 v[220:221], s[46:47], 0, v[136:137]
	s_mov_b32 m0, s48
	v_lshl_add_u64 v[222:223], s[14:15], 0, v[134:135]
	global_load_lds_dwordx4 v[220:221], off
	v_lshl_add_u64 v[220:221], s[46:47], 0, v[2:3]
	s_add_i32 m0, s48, 0x2000
	s_nop 0
	global_load_lds_dwordx4 v[220:221], off
	v_lshl_add_u64 v[220:221], s[14:15], 0, v[138:139]
	s_mov_b32 m0, s18
	s_nop 0
	global_load_lds_dwordx4 v[220:221], off
	s_mov_b32 m0, s19
	s_nop 0
	global_load_lds_dwordx4 v[222:223], off
	s_waitcnt vmcnt(8)
	s_waitcnt lgkmcnt(0)
	s_barrier
; #define PG8_STAGE(bufoff, gbase, voff) do { _Pragma("unroll") for (int _i = 0; _i < 2; ++_i) \
;         __builtin_amdgcn_global_load_lds((const unsigned*)((const char*)(gbase) + (voff)[_i]), (PG8_LAS unsigned*)(lds + (bufoff) + ldsw + _i * 8192), 16, 0, 0); } while (0)
; #define PG8_LDA(dst, b, h) do { _Pragma("unroll") for (int m = 0; m < 4; ++m) _Pragma("unroll") for (int k = 0; k < 2; ++k) dst[m][k] = *(const PG8_LAS bf16x8*)(lds + PG8_SA(b, h) + aoff + m * 2048 + k * 1024); } while (0)
; #define PG8_LDB(dst, b, h) do { _Pragma("unroll") for (int n = 0; n < 2; ++n) _Pragma("unroll") for (int k = 0; k < 2; ++k) dst[n][k] = *(const PG8_LAS bf16x8*)(lds + PG8_SB(b, h) + boff + n * 2048 + k * 1024); } while (0)
; #define PG8_MMA(ai, bj, At, Bt) do { __builtin_amdgcn_s_setprio(1); _Pragma("unroll") for (int m = 0; m < 4; ++m) _Pragma("unroll") for (int n = 0; n < 2; ++n) _Pragma("unroll") for (int k = 0; k < 2; ++k) \
;         acc[ai][bj][m][n] = __builtin_amdgcn_mfma_f32_16x16x32_bf16(Bt[n][k], At[m][k], acc[ai][bj][m][n], 0, 0, 0); __builtin_amdgcn_s_setprio(0); } while (0)
; #define PG8_WAIT_V(n) asm volatile("s_waitcnt vmcnt(" #n ")" ::: "memory")
; #define PG8_WAIT_L(n) asm volatile("s_waitcnt lgkmcnt(" #n ")" ::: "memory")
; #define PG8_BAR __builtin_amdgcn_s_barrier()
; #define PG8_SCHED __builtin_amdgcn_sched_barrier(0)
; template <class Epi, class Sched, bool ALIGN_EPI = false, bool SP2 = false>
; __device__ __forceinline__ void gemm_phase(PG8_LAS unsigned char* lds, const Gemm g, const Sched& S, const Epi& E, const int tid_in) {
;     ...
;             PG8_WAIT_V(8); PG8_WAIT_L(0); PG8_BAR; PG8_MMA(1, 0, At, B0); PG8_MMA(1, 1, At, B1); PG8_BAR; PG8_SCHED;
;             PG8_LDB(B0, 1, 0); PG8_LDB(B1, 1, 1); PG8_SCHED; PG8_LDA(At, 1, 0); PG8_STAGE(PG8_SA(0, 1), a2 + hstep, voffA);
;             PG8_WAIT_V(8); PG8_WAIT_L(0); PG8_BAR; PG8_MMA(0, 0, At, B0); PG8_MMA(0, 1, At, B1); PG8_BAR; PG8_SCHED;
	v_mfma_f32_16x16x32_bf16 v[66:69], v[150:153], v[182:185], 0
	v_mfma_f32_16x16x32_bf16 v[66:69], v[154:157], v[186:189], v[66:69]
	v_mfma_f32_16x16x32_bf16 v[50:53], v[150:153], v[190:193], 0
	v_mfma_f32_16x16x32_bf16 v[50:53], v[154:157], v[198:201], v[50:53]
	v_mfma_f32_16x16x32_bf16 v[34:37], v[150:153], v[202:205], 0
	v_mfma_f32_16x16x32_bf16 v[34:37], v[154:157], v[206:209], v[34:37]
	v_mfma_f32_16x16x32_bf16 v[18:21], v[150:153], v[210:213], 0
	v_mfma_f32_16x16x32_bf16 v[18:21], v[154:157], v[214:217], v[18:21]
	v_mfma_f32_16x16x32_bf16 v[62:65], v[158:161], v[182:185], 0
	v_mfma_f32_16x16x32_bf16 v[62:65], v[162:165], v[186:189], v[62:65]
	v_mfma_f32_16x16x32_bf16 v[46:49], v[158:161], v[190:193], 0
	v_mfma_f32_16x16x32_bf16 v[46:49], v[162:165], v[198:201], v[46:49]
	v_mfma_f32_16x16x32_bf16 v[30:33], v[158:161], v[202:205], 0
	v_mfma_f32_16x16x32_bf16 v[30:33], v[162:165], v[206:209], v[30:33]
	v_mfma_f32_16x16x32_bf16 v[14:17], v[158:161], v[210:213], 0
	v_mfma_f32_16x16x32_bf16 v[14:17], v[162:165], v[214:217], v[14:17]
	v_mfma_f32_16x16x32_bf16 v[58:61], v[166:169], v[182:185], 0
	v_mfma_f32_16x16x32_bf16 v[58:61], v[170:173], v[186:189], v[58:61]
	v_mfma_f32_16x16x32_bf16 v[42:45], v[166:169], v[190:193], 0
	v_mfma_f32_16x16x32_bf16 v[42:45], v[170:173], v[198:201], v[42:45]
	v_mfma_f32_16x16x32_bf16 v[26:29], v[166:169], v[202:205], 0
	v_mfma_f32_16x16x32_bf16 v[26:29], v[170:173], v[206:209], v[26:29]
	v_mfma_f32_16x16x32_bf16 v[10:13], v[166:169], v[210:213], 0
	v_mfma_f32_16x16x32_bf16 v[10:13], v[170:173], v[214:217], v[10:13]
	v_mfma_f32_16x16x32_bf16 v[54:57], v[174:177], v[182:185], 0
	v_mfma_f32_16x16x32_bf16 v[54:57], v[178:181], v[186:189], v[54:57]
	v_mfma_f32_16x16x32_bf16 v[38:41], v[174:177], v[190:193], 0
	v_mfma_f32_16x16x32_bf16 v[38:41], v[178:181], v[198:201], v[38:41]
	v_mfma_f32_16x16x32_bf16 v[22:25], v[174:177], v[202:205], 0
	v_mfma_f32_16x16x32_bf16 v[22:25], v[178:181], v[206:209], v[22:25]
	v_mfma_f32_16x16x32_bf16 v[6:9], v[174:177], v[210:213], 0
	v_mfma_f32_16x16x32_bf16 v[6:9], v[178:181], v[214:217], v[6:9]
	s_barrier
	s_add_i32 s46, 0, 0x18000
	v_add_u32_e32 v149, s46, v146
	s_add_i32 s47, 0, 0x1c000
	ds_read_b128 v[150:153], v149
	ds_read_b128 v[154:157], v149 offset:1024
	ds_read_b128 v[158:161], v149 offset:2048
	ds_read_b128 v[162:165], v149 offset:3072
	v_add_u32_e32 v149, s47, v146
	ds_read_b128 v[166:169], v149
	ds_read_b128 v[170:173], v149 offset:1024
	ds_read_b128 v[174:177], v149 offset:2048
	ds_read_b128 v[178:181], v149 offset:3072
	s_add_u32 s14, s14, 0x40000
	s_addc_u32 s15, s15, 0
	s_mov_b32 m0, s22
	v_lshl_add_u64 v[224:225], s[14:15], 0, v[138:139]
	ds_read_b128 v[182:185], v148 offset:32768
	ds_read_b128 v[186:189], v148 offset:33792
	ds_read_b128 v[190:193], v148 offset:34816
	ds_read_b128 v[198:201], v148 offset:35840
	ds_read_b128 v[202:205], v148 offset:36864
	ds_read_b128 v[206:209], v148 offset:37888
	ds_read_b128 v[210:213], v148 offset:38912
	ds_read_b128 v[214:217], v148 offset:39936
	global_load_lds_dwordx4 v[224:225], off
	v_lshl_add_u64 v[224:225], s[14:15], 0, v[134:135]
	s_mov_b32 m0, s23
	s_nop 0
	global_load_lds_dwordx4 v[224:225], off
	s_waitcnt vmcnt(8)
	s_waitcnt lgkmcnt(0)
	s_barrier
; #define PG8_STAGE(bufoff, gbase, voff) do { _Pragma("unroll") for (int _i = 0; _i < 2; ++_i) \
;         __builtin_amdgcn_global_load_lds((const unsigned*)((const char*)(gbase) + (voff)[_i]), (PG8_LAS unsigned*)(lds + (bufoff) + ldsw + _i * 8192), 16, 0, 0); } while (0)
; #define PG8_LDA(dst, b, h) do { _Pragma("unroll") for (int m = 0; m < 4; ++m) _Pragma("unroll") for (int k = 0; k < 2; ++k) dst[m][k] = *(const PG8_LAS bf16x8*)(lds + PG8_SA(b, h) + aoff + m * 2048 + k * 1024); } while (0)
; #define PG8_MMA(ai, bj, At, Bt) do { __builtin_amdgcn_s_setprio(1); _Pragma("unroll") for (int m = 0; m < 4; ++m) _Pragma("unroll") for (int n = 0; n < 2; ++n) _Pragma("unroll") for (int k = 0; k < 2; ++k) \
;         acc[ai][bj][m][n] = __builtin_amdgcn_mfma_f32_16x16x32_bf16(Bt[n][k], At[m][k], acc[ai][bj][m][n], 0, 0, 0); __builtin_amdgcn_s_setprio(0); } while (0)
; #define PG8_WAIT_V(n) asm volatile("s_waitcnt vmcnt(" #n ")" ::: "memory")
; #define PG8_WAIT_L(n) asm volatile("s_waitcnt lgkmcnt(" #n ")" ::: "memory")
; #define PG8_BAR __builtin_amdgcn_s_barrier()
; #define PG8_SCHED __builtin_amdgcn_sched_barrier(0)
; template <class Epi, class Sched, bool ALIGN_EPI = false, bool SP2 = false>
; __device__ __forceinline__ void gemm_phase(PG8_LAS unsigned char* lds, const Gemm g, const Sched& S, const Epi& E, const int tid_in) {
;     ...
;             PG8_WAIT_V(8); PG8_WAIT_L(0); PG8_BAR; PG8_MMA(0, 0, At, B0); PG8_MMA(0, 1, At, B1); PG8_BAR; PG8_SCHED;
;             PG8_LDA(At, 1, 1); PG8_STAGE(PG8_SB(1, 0), b3, voffB); PG8_STAGE(PG8_SB(1, 1), b3 + hstep, voffB); PG8_STAGE(PG8_SA(1, 0), a3, voffA);
;             PG8_WAIT_V(8); PG8_WAIT_L(0); PG8_BAR; PG8_MMA(1, 0, At, B0); PG8_MMA(1, 1, At, B1); PG8_BAR; PG8_SCHED;
;     __device__ __forceinline__ void operator()(const f32x4 (&acc)[2][2][4][2], const Unit& u, int wr, int wc, int fr, int fq) const {
;     ...
;             for (int m = 0; m < 4; ++m) rs[ai][m] = rowss[row0 + ai * HALF + m * 16];
	v_mfma_f32_16x16x32_bf16 v[130:133], v[150:153], v[182:185], v[130:133]
	v_mfma_f32_16x16x32_bf16 v[130:133], v[154:157], v[186:189], v[130:133]
	v_mfma_f32_16x16x32_bf16 v[114:117], v[150:153], v[190:193], v[114:117]
	v_mfma_f32_16x16x32_bf16 v[114:117], v[154:157], v[198:201], v[114:117]
	v_mfma_f32_16x16x32_bf16 v[98:101], v[150:153], v[202:205], v[98:101]
	v_mfma_f32_16x16x32_bf16 v[98:101], v[154:157], v[206:209], v[98:101]
	v_mfma_f32_16x16x32_bf16 v[82:85], v[150:153], v[210:213], v[82:85]
	v_mfma_f32_16x16x32_bf16 v[82:85], v[154:157], v[214:217], v[82:85]
	v_mfma_f32_16x16x32_bf16 v[126:129], v[158:161], v[182:185], v[126:129]
	v_mfma_f32_16x16x32_bf16 v[126:129], v[162:165], v[186:189], v[126:129]
	v_mfma_f32_16x16x32_bf16 v[106:109], v[158:161], v[190:193], v[106:109]
	v_mfma_f32_16x16x32_bf16 v[106:109], v[162:165], v[198:201], v[106:109]
	v_mfma_f32_16x16x32_bf16 v[94:97], v[158:161], v[202:205], v[94:97]
	v_mfma_f32_16x16x32_bf16 v[94:97], v[162:165], v[206:209], v[94:97]
	v_mfma_f32_16x16x32_bf16 v[78:81], v[158:161], v[210:213], v[78:81]
	v_mfma_f32_16x16x32_bf16 v[78:81], v[162:165], v[214:217], v[78:81]
	v_mfma_f32_16x16x32_bf16 v[122:125], v[166:169], v[182:185], v[122:125]
	v_mfma_f32_16x16x32_bf16 v[122:125], v[170:173], v[186:189], v[122:125]
	v_mfma_f32_16x16x32_bf16 v[110:113], v[166:169], v[190:193], v[110:113]
	v_mfma_f32_16x16x32_bf16 v[110:113], v[170:173], v[198:201], v[110:113]
	v_mfma_f32_16x16x32_bf16 v[90:93], v[166:169], v[202:205], v[90:93]
	v_mfma_f32_16x16x32_bf16 v[90:93], v[170:173], v[206:209], v[90:93]
	v_mfma_f32_16x16x32_bf16 v[74:77], v[166:169], v[210:213], v[74:77]
	v_mfma_f32_16x16x32_bf16 v[74:77], v[170:173], v[214:217], v[74:77]
	v_mfma_f32_16x16x32_bf16 v[118:121], v[174:177], v[182:185], v[118:121]
	v_mfma_f32_16x16x32_bf16 v[118:121], v[178:181], v[186:189], v[118:121]
	v_mfma_f32_16x16x32_bf16 v[102:105], v[174:177], v[190:193], v[102:105]
	v_mfma_f32_16x16x32_bf16 v[102:105], v[178:181], v[198:201], v[102:105]
	v_mfma_f32_16x16x32_bf16 v[86:89], v[174:177], v[202:205], v[86:89]
	v_mfma_f32_16x16x32_bf16 v[86:89], v[178:181], v[206:209], v[86:89]
	v_mfma_f32_16x16x32_bf16 v[70:73], v[174:177], v[210:213], v[70:73]
	v_mfma_f32_16x16x32_bf16 v[70:73], v[178:181], v[214:217], v[70:73]
	s_barrier
	s_add_i32 s14, s46, s17
	v_lshl_add_u64 v[144:145], v[144:145], 0, s[28:29]
	s_mov_b32 m0, s14
	ds_read_b128 v[182:185], v148 offset:49152
	ds_read_b128 v[186:189], v148 offset:50176
	ds_read_b128 v[190:193], v148 offset:51200
	ds_read_b128 v[198:201], v148 offset:52224
	ds_read_b128 v[202:205], v148 offset:53248
	ds_read_b128 v[206:209], v148 offset:54272
	ds_read_b128 v[210:213], v148 offset:55296
	ds_read_b128 v[214:217], v148 offset:56320
	global_load_lds_dwordx4 v[144:145], off
	s_add_i32 m0, s14, 0x2000
	s_add_u32 s12, s12, 0x40080
	v_lshl_add_u64 v[144:145], v[218:219], 0, s[28:29]
	s_addc_u32 s13, s13, 0
	s_add_i32 s14, s47, s17
	global_load_lds_dwordx4 v[144:145], off
	v_lshl_add_u64 v[144:145], s[12:13], 0, v[136:137]
	s_mov_b32 m0, s14
	s_nop 0
	global_load_lds_dwordx4 v[144:145], off
	v_lshl_add_u64 v[144:145], s[12:13], 0, v[2:3]
	s_add_i32 m0, s14, 0x2000
	s_nop 0
	global_load_lds_dwordx4 v[144:145], off
	v_lshl_add_u64 v[144:145], v[220:221], 0, s[28:29]
	s_mov_b32 m0, s26
	s_nop 0
	global_load_lds_dwordx4 v[144:145], off
	v_lshl_add_u64 v[144:145], v[222:223], 0, s[28:29]
	s_mov_b32 m0, s27
	s_nop 0
	global_load_lds_dwordx4 v[144:145], off
	s_waitcnt vmcnt(8)
	s_waitcnt lgkmcnt(0)
	s_cmp_lg_u32 s45, 12
	s_cbranch_scc1 .Lrs_gu_skip_pgu
	v_lshl_add_u32 v144, s40, 8, v5
	v_ashrrev_i32_e32 v145, 31, v144
	v_lshl_add_u64 v[144:145], v[144:145], 2, s[6:7]
	global_load_dword v226, v[144:145], off
	global_load_dword v227, v[144:145], off offset:64
	global_load_dword v228, v[144:145], off offset:128
	global_load_dword v229, v[144:145], off offset:192
	global_load_dword v238, v[144:145], off offset:512
	global_load_dword v239, v[144:145], off offset:576
	global_load_dword v240, v[144:145], off offset:640
	global_load_dword v241, v[144:145], off offset:704

; #define PG8_STAGE(bufoff, gbase, voff) do { _Pragma("unroll") for (int _i = 0; _i < 2; ++_i) \
;         __builtin_amdgcn_global_load_lds((const unsigned*)((const char*)(gbase) + (voff)[_i]), (PG8_LAS unsigned*)(lds + (bufoff) + ldsw + _i * 8192), 16, 0, 0); } while (0)
; #define PG8_BAR __builtin_amdgcn_s_barrier()
; template <class Epi, class Sched, bool ALIGN_EPI = false, bool SP2 = false>
; __device__ __forceinline__ void gemm_phase(PG8_LAS unsigned char* lds, const Gemm g, const Sched& S, const Epi& E, const int tid_in) {
;     const int tid = tid_in, wid = __builtin_amdgcn_readfirstlane(tid >> 6), lane = tid & 63, wr = wid >> 2, wc = wid & 3, fr = lane & 15, fq = lane >> 4;
;     const int K = g.K, nt = K / BK;
;     unsigned voffA[2], voffB[2];
; #pragma unroll
;     for (int i = 0; i < 2; ++i) { int R, C; stage_rc(tid * 16 + i * 8192, R, C); const int Rb = Epi::PERM ? ((R & ~31) + perm32(R & 31)) : R;
;         voffA[i] = (unsigned)(R * K + C) * 2u; voffB[i] = (unsigned)(Rb * K + C) * 2u; }
;     const size_t kstep = (size_t)(BK * 2);
;     const size_t hstep = (size_t)HALF * K * 2;
;     const size_t tstep = 2 * hstep;
;     const unsigned ldsw = (unsigned)wid * 1024u;
;     const int aoff = lds_byte(wr * 64 + fr, fq * 8), boff = lds_byte(wc * 32 + fr, fq * 8);
;     ...
;     Unit cur, nxt; int ui = 0;
;     if (!S.next(0, cur)) return;
;     f32x4 acc[2][2][4][2];
; #pragma unroll
;     for (int a = 0; a < 2; ++a)
; #pragma unroll
;         for (int b = 0; b < 2; ++b)
; #pragma unroll
;             for (int m = 0; m < 4; ++m)
; #pragma unroll
;                 for (int n = 0; n < 2; ++n) acc[a][b][m][n] = (f32x4){0.f, 0.f, 0.f, 0.f};
;     bf16x8 At[4][2], B0[2][2], B1[2][2];
;     const char* cA = (const char*)g.A + (size_t)cur.pm * tstep; const char* cB = (const char*)g.Bt + (size_t)cur.pn * tstep;
;     S.a_ready(cur);
;     if constexpr (SP2) {
;         PG8_STAGE(PG8_SB(0, 0), cB, voffB); PG8_STAGE(PG8_SB(0, 1), cB + hstep, voffB); PG8_STAGE(PG8_SA(0, 0), cA, voffA); PG8_STAGE(PG8_SA(0, 1), cA + hstep, voffA);
;         if (wr == 1) PG8_BAR;
.LBB0_160:
	v_bfe_u32 v3, v244, 4, 2
	v_readfirstlane_b32 s14, v244
	v_and_b32_e32 v245, 15, v244
	s_and_b64 vcc, exec, s[36:37]
	s_waitcnt vmcnt(6)
	v_lshlrev_b32_e32 v5, 4, v3
	s_cbranch_vccnz .LBB0_188
	s_waitcnt vmcnt(0) lgkmcnt(0)
	v_lshlrev_b32_e32 v9, 4, v244
	v_add_u32_e32 v6, 0x2000, v9
	v_ashrrev_i32_e32 v7, 31, v6
	v_lshrrev_b32_e32 v7, 22, v7
	v_add_u32_e32 v7, v6, v7
	v_ashrrev_i32_e32 v7, 10, v7
	v_mul_i32_i24_e32 v8, 0x400, v7
	v_sub_u32_e32 v6, v6, v8
	v_lshrrev_b32_e32 v8, 4, v6
	v_bitop3_b32 v8, v8, v6, 32 bitop3:0x6c
	v_ashrrev_i32_e32 v6, 31, v8
	v_lshrrev_b32_e32 v6, 26, v6
	v_add_u32_e32 v10, v8, v6
	v_lshlrev_b32_e32 v11, 3, v7
	v_ashrrev_i32_e32 v6, 6, v10
	v_and_b32_e32 v11, -16, v11
	v_add_u32_e32 v11, v6, v11
	v_and_b32_e32 v6, 3, v6
	s_mov_b32 s0, 0x7fffffe0
	v_lshrrev_b32_e32 v12, 2, v11
	v_lshlrev_b32_e32 v13, 1, v11
	v_and_or_b32 v6, v11, s0, v6
	v_and_b32_e32 v12, 4, v12
	v_and_b32_e32 v13, 24, v13
	v_or3_b32 v6, v6, v12, v13
	v_mul_lo_u32 v12, v6, s3
	v_lshlrev_b32_e32 v6, 5, v7
	v_and_b32_e32 v7, 0xc0, v10
	v_sub_u32_e32 v7, v8, v7
	v_ashrrev_i16_sdwa v7, v230, sext(v7) dst_sel:DWORD dst_unused:UNUSED_PAD src0_sel:DWORD src1_sel:BYTE_0
	v_and_b32_e32 v6, 32, v6
	v_bfe_i32 v7, v7, 0, 16
	v_add_u32_e32 v10, v6, v7
	v_mul_lo_u32 v8, v11, s3
	v_add_lshl_u32 v198, v12, v10, 1
	v_add_lshl_u32 v200, v10, v8, 1
	v_bfe_i32 v10, v244, 27, 1
	v_lshrrev_b32_e32 v10, 22, v10
	v_add_u32_e32 v10, v9, v10
	v_and_b32_e32 v10, 0xfffffc00, v10
	v_sub_u32_e32 v9, v9, v10
	v_lshrrev_b32_e32 v10, 4, v9
	v_ashrrev_i32_e32 v12, 31, v244
	v_bitop3_b32 v10, v10, v9, 32 bitop3:0x6c
	v_lshrrev_b32_e32 v12, 26, v12
	v_ashrrev_i32_e32 v9, 31, v10
	v_add_u32_e32 v12, v244, v12
	v_lshrrev_b32_e32 v9, 26, v9
	v_ashrrev_i32_e32 v12, 6, v12
	v_add_u32_e32 v11, v10, v9
	v_lshlrev_b32_e32 v13, 3, v12
	v_ashrrev_i32_e32 v9, 6, v11
	v_and_b32_e32 v13, -16, v13
	v_add_u32_e32 v13, v9, v13
	v_and_b32_e32 v9, 3, v9
	s_lshl_b32 s16, s3, 9
	v_and_or_b32 v9, v13, s0, v9
	v_lshrrev_b32_e32 v14, 2, v13
	v_lshlrev_b32_e32 v15, 1, v13
	v_readlane_b32 s0, v252, 50
	v_and_b32_e32 v14, 4, v14
	v_and_b32_e32 v15, 24, v15
	v_and_b32_e32 v11, 0xc0, v11
	s_mul_hi_i32 s11, s16, s0
	s_mul_i32 s10, s16, s0
	v_readlane_b32 s0, v252, 52
	s_ashr_i32 s15, s14, 6
	v_or3_b32 v9, v9, v14, v15
	v_sub_u32_e32 v10, v10, v11
	v_readlane_b32 s1, v252, 53
	s_mov_b32 s12, s0
	s_ashr_i32 s31, s14, 8
	s_lshl_b32 s62, s3, 8
	s_lshl_b32 s17, s15, 10
	v_mul_lo_u32 v14, v9, s3
	v_lshlrev_b32_e32 v9, 5, v12
	v_ashrrev_i16_sdwa v10, v230, sext(v10) dst_sel:DWORD dst_unused:UNUSED_PAD src0_sel:DWORD src1_sel:BYTE_0
	s_mul_i32 s1, s16, s12
	v_and_b32_e32 v9, 32, v9
	v_bfe_i32 v10, v10, 0, 16
	s_mul_hi_i32 s0, s16, s0
	s_add_u32 s12, s24, s1
	v_add_u32_e32 v12, v9, v10
	s_addc_u32 s13, s25, s0
	s_add_i32 s18, s17, 0
	v_add_lshl_u32 v202, v14, v12, 1
	s_add_i32 m0, s18, 0x10000
	s_mov_b32 s68, s19
	global_load_lds_dwordx4 v202, s[12:13]
	s_add_i32 m0, s18, 0x12000
	s_add_u32 s0, s12, s62
	global_load_lds_dwordx4 v198, s[12:13]
	s_addc_u32 s1, s13, 0
	s_add_i32 m0, s18, 0x14000
	v_mul_lo_u32 v11, v13, s3
	global_load_lds_dwordx4 v202, s[0:1]
	s_add_i32 m0, s18, 0x16000
	s_add_u32 s10, s20, s10
	s_addc_u32 s11, s21, s11
	s_add_i32 s19, s18, 0x2000
	v_add_lshl_u32 v204, v12, v11, 1
	global_load_lds_dwordx4 v198, s[0:1]
	s_mov_b32 m0, s18
	s_add_u32 s26, s10, s62
	global_load_lds_dwordx4 v204, s[10:11]
	s_mov_b32 m0, s19
	s_addc_u32 s27, s11, 0
	s_add_i32 s22, s18, 0x4000
	global_load_lds_dwordx4 v200, s[10:11]
	s_mov_b32 m0, s22
	s_add_i32 s23, s18, 0x6000
	global_load_lds_dwordx4 v204, s[26:27]
	s_mov_b32 m0, s23
	s_cmp_eq_u32 s31, 1
	global_load_lds_dwordx4 v200, s[26:27]
	s_cselect_b64 s[34:35], -1, 0
	s_cmp_lg_u32 s31, 1
	s_cbranch_scc1 .LBB0_163
	s_barrier
	s_setprio 1
